# c13 with the eight GEMM inner-loop heads aligned to 64 bytes (.p2align 6); no other change
# baseline (speedup 1.0000x reference)
.LBB0_165:
	s_ashr_i32 s29, s28, 31
	s_lshl_b64 s[30:31], s[28:29], 19
	s_add_u32 s30, s27, s30
	s_addc_u32 s31, s44, s31
	s_and_b64 s[34:35], s[4:5], exec
	s_cselect_b32 s7, s31, s39
	s_cselect_b32 s29, s30, s38
	s_ashr_i32 s19, s18, 31
	s_lshl_b64 s[34:35], s[18:19], 19
	s_add_u32 s34, s45, s34
	s_addc_u32 s35, s46, s35
	s_and_b64 s[42:43], s[4:5], exec
	s_cselect_b32 s19, s35, s41
	s_cselect_b32 s61, s34, s40
	s_add_u32 s38, s38, 0x40080
	s_addc_u32 s39, s39, 0
	s_add_u32 s63, s40, 0x100
	v_mov_b32_e32 v0, 0
	s_addc_u32 s65, s41, 0
	s_mov_b32 s66, -2
	v_mov_b32_e32 v1, v0
	v_mov_b32_e32 v2, v0
	v_mov_b32_e32 v3, v0
	v_mov_b32_e32 v4, v0
	v_mov_b32_e32 v5, v0
	v_mov_b32_e32 v6, v0
	v_mov_b32_e32 v7, v0
	v_mov_b32_e32 v16, v0
	v_mov_b32_e32 v17, v0
	v_mov_b32_e32 v18, v0
	v_mov_b32_e32 v19, v0
	v_mov_b32_e32 v20, v0
	v_mov_b32_e32 v21, v0
	v_mov_b32_e32 v22, v0
	v_mov_b32_e32 v23, v0
	v_mov_b32_e32 v32, v0
	v_mov_b32_e32 v33, v0
	v_mov_b32_e32 v34, v0
	v_mov_b32_e32 v35, v0
	v_mov_b32_e32 v36, v0
	v_mov_b32_e32 v37, v0
	v_mov_b32_e32 v38, v0
	v_mov_b32_e32 v39, v0
	v_mov_b32_e32 v48, v0
	v_mov_b32_e32 v49, v0
	v_mov_b32_e32 v50, v0
	v_mov_b32_e32 v51, v0
	v_mov_b32_e32 v52, v0
	v_mov_b32_e32 v53, v0
	v_mov_b32_e32 v54, v0
	v_mov_b32_e32 v55, v0
	v_mov_b32_e32 v8, v0
	v_mov_b32_e32 v9, v0
	v_mov_b32_e32 v10, v0
	v_mov_b32_e32 v11, v0
	v_mov_b32_e32 v12, v0
	v_mov_b32_e32 v13, v0
	v_mov_b32_e32 v14, v0
	v_mov_b32_e32 v15, v0
	v_mov_b32_e32 v24, v0
	v_mov_b32_e32 v25, v0
	v_mov_b32_e32 v26, v0
	v_mov_b32_e32 v27, v0
	v_mov_b32_e32 v28, v0
	v_mov_b32_e32 v29, v0
	v_mov_b32_e32 v30, v0
	v_mov_b32_e32 v31, v0
	v_mov_b32_e32 v40, v0
	v_mov_b32_e32 v41, v0
	v_mov_b32_e32 v42, v0
	v_mov_b32_e32 v43, v0
	v_mov_b32_e32 v44, v0
	v_mov_b32_e32 v45, v0
	v_mov_b32_e32 v46, v0
	v_mov_b32_e32 v47, v0
	v_mov_b32_e32 v56, v0
	v_mov_b32_e32 v57, v0
	v_mov_b32_e32 v58, v0
	v_mov_b32_e32 v59, v0
	v_mov_b32_e32 v60, v0
	v_mov_b32_e32 v61, v0
	v_mov_b32_e32 v62, v0
	v_mov_b32_e32 v63, v0
	v_mov_b32_e32 v64, v0
	v_mov_b32_e32 v65, v0
	v_mov_b32_e32 v66, v0
	v_mov_b32_e32 v67, v0
	v_mov_b32_e32 v68, v0
	v_mov_b32_e32 v69, v0
	v_mov_b32_e32 v70, v0
	v_mov_b32_e32 v71, v0
	v_mov_b32_e32 v80, v0
	v_mov_b32_e32 v81, v0
	v_mov_b32_e32 v82, v0
	v_mov_b32_e32 v83, v0
	v_mov_b32_e32 v84, v0
	v_mov_b32_e32 v85, v0
	v_mov_b32_e32 v86, v0
	v_mov_b32_e32 v87, v0
	v_mov_b32_e32 v96, v0
	v_mov_b32_e32 v97, v0
	v_mov_b32_e32 v98, v0
	v_mov_b32_e32 v99, v0
	v_mov_b32_e32 v100, v0
	v_mov_b32_e32 v101, v0
	v_mov_b32_e32 v102, v0
	v_mov_b32_e32 v103, v0
	v_mov_b32_e32 v112, v0
	v_mov_b32_e32 v113, v0
	v_mov_b32_e32 v114, v0
	v_mov_b32_e32 v115, v0
	v_mov_b32_e32 v116, v0
	v_mov_b32_e32 v117, v0
	v_mov_b32_e32 v118, v0
	v_mov_b32_e32 v119, v0
	v_mov_b32_e32 v72, v0
	v_mov_b32_e32 v73, v0
	v_mov_b32_e32 v74, v0
	v_mov_b32_e32 v75, v0
	v_mov_b32_e32 v76, v0
	v_mov_b32_e32 v77, v0
	v_mov_b32_e32 v78, v0
	v_mov_b32_e32 v79, v0
	v_mov_b32_e32 v88, v0
	v_mov_b32_e32 v89, v0
	v_mov_b32_e32 v90, v0
	v_mov_b32_e32 v91, v0
	v_mov_b32_e32 v92, v0
	v_mov_b32_e32 v93, v0
	v_mov_b32_e32 v94, v0
	v_mov_b32_e32 v95, v0
	v_mov_b32_e32 v104, v0
	v_mov_b32_e32 v105, v0
	v_mov_b32_e32 v106, v0
	v_mov_b32_e32 v107, v0
	v_mov_b32_e32 v108, v0
	v_mov_b32_e32 v109, v0
	v_mov_b32_e32 v110, v0
	v_mov_b32_e32 v111, v0
	v_mov_b32_e32 v120, v0
	v_mov_b32_e32 v121, v0
	v_mov_b32_e32 v122, v0
	v_mov_b32_e32 v123, v0
	v_mov_b32_e32 v124, v0
	v_mov_b32_e32 v125, v0
	v_mov_b32_e32 v126, v0
	v_mov_b32_e32 v127, v0
	.p2align 6

.LBB0_549:
	s_ashr_i32 s39, s38, 31
	s_lshl_b64 s[44:45], s[38:39], 19
	s_add_u32 s44, s54, s44
	s_addc_u32 s45, s55, s45
	s_and_b64 s[46:47], s[4:5], exec
	s_cselect_b32 s39, s45, s49
	s_cselect_b32 s78, s44, s48
	s_ashr_i32 s41, s40, 31
	s_lshl_b64 s[46:47], s[40:41], 19
	s_add_u32 s46, s56, s46
	s_addc_u32 s47, s57, s47
	s_and_b64 s[52:53], s[4:5], exec
	s_cselect_b32 s41, s47, s51
	s_cselect_b32 s79, s46, s50
	s_add_u32 s48, s48, 0x40080
	s_addc_u32 s49, s49, 0
	s_add_u32 s80, s50, 0x100
	v_mov_b32_e32 v0, 0
	s_addc_u32 s81, s51, 0
	s_mov_b32 s82, -2
	v_mov_b32_e32 v1, v0
	v_mov_b32_e32 v2, v0
	v_mov_b32_e32 v3, v0
	v_mov_b32_e32 v4, v0
	v_mov_b32_e32 v5, v0
	v_mov_b32_e32 v6, v0
	v_mov_b32_e32 v7, v0
	v_mov_b32_e32 v8, v0
	v_mov_b32_e32 v9, v0
	v_mov_b32_e32 v10, v0
	v_mov_b32_e32 v11, v0
	v_mov_b32_e32 v12, v0
	v_mov_b32_e32 v13, v0
	v_mov_b32_e32 v14, v0
	v_mov_b32_e32 v15, v0
	v_mov_b32_e32 v24, v0
	v_mov_b32_e32 v25, v0
	v_mov_b32_e32 v26, v0
	v_mov_b32_e32 v27, v0
	v_mov_b32_e32 v28, v0
	v_mov_b32_e32 v29, v0
	v_mov_b32_e32 v30, v0
	v_mov_b32_e32 v31, v0
	v_mov_b32_e32 v40, v0
	v_mov_b32_e32 v41, v0
	v_mov_b32_e32 v42, v0
	v_mov_b32_e32 v43, v0
	v_mov_b32_e32 v44, v0
	v_mov_b32_e32 v45, v0
	v_mov_b32_e32 v46, v0
	v_mov_b32_e32 v47, v0
	v_mov_b32_e32 v16, v0
	v_mov_b32_e32 v17, v0
	v_mov_b32_e32 v18, v0
	v_mov_b32_e32 v19, v0
	v_mov_b32_e32 v20, v0
	v_mov_b32_e32 v21, v0
	v_mov_b32_e32 v22, v0
	v_mov_b32_e32 v23, v0
	v_mov_b32_e32 v32, v0
	v_mov_b32_e32 v33, v0
	v_mov_b32_e32 v34, v0
	v_mov_b32_e32 v35, v0
	v_mov_b32_e32 v36, v0
	v_mov_b32_e32 v37, v0
	v_mov_b32_e32 v38, v0
	v_mov_b32_e32 v39, v0
	v_mov_b32_e32 v48, v0
	v_mov_b32_e32 v49, v0
	v_mov_b32_e32 v50, v0
	v_mov_b32_e32 v51, v0
	v_mov_b32_e32 v52, v0
	v_mov_b32_e32 v53, v0
	v_mov_b32_e32 v54, v0
	v_mov_b32_e32 v55, v0
	v_mov_b32_e32 v56, v0
	v_mov_b32_e32 v57, v0
	v_mov_b32_e32 v58, v0
	v_mov_b32_e32 v59, v0
	v_mov_b32_e32 v60, v0
	v_mov_b32_e32 v61, v0
	v_mov_b32_e32 v62, v0
	v_mov_b32_e32 v63, v0
	v_mov_b32_e32 v64, v0
	v_mov_b32_e32 v65, v0
	v_mov_b32_e32 v66, v0
	v_mov_b32_e32 v67, v0
	v_mov_b32_e32 v68, v0
	v_mov_b32_e32 v69, v0
	v_mov_b32_e32 v70, v0
	v_mov_b32_e32 v71, v0
	v_mov_b32_e32 v72, v0
	v_mov_b32_e32 v73, v0
	v_mov_b32_e32 v74, v0
	v_mov_b32_e32 v75, v0
	v_mov_b32_e32 v76, v0
	v_mov_b32_e32 v77, v0
	v_mov_b32_e32 v78, v0
	v_mov_b32_e32 v79, v0
	v_mov_b32_e32 v88, v0
	v_mov_b32_e32 v89, v0
	v_mov_b32_e32 v90, v0
	v_mov_b32_e32 v91, v0
	v_mov_b32_e32 v92, v0
	v_mov_b32_e32 v93, v0
	v_mov_b32_e32 v94, v0
	v_mov_b32_e32 v95, v0
	v_mov_b32_e32 v104, v0
	v_mov_b32_e32 v105, v0
	v_mov_b32_e32 v106, v0
	v_mov_b32_e32 v107, v0
	v_mov_b32_e32 v108, v0
	v_mov_b32_e32 v109, v0
	v_mov_b32_e32 v110, v0
	v_mov_b32_e32 v111, v0
	v_mov_b32_e32 v80, v0
	v_mov_b32_e32 v81, v0
	v_mov_b32_e32 v82, v0
	v_mov_b32_e32 v83, v0
	v_mov_b32_e32 v84, v0
	v_mov_b32_e32 v85, v0
	v_mov_b32_e32 v86, v0
	v_mov_b32_e32 v87, v0
	v_mov_b32_e32 v96, v0
	v_mov_b32_e32 v97, v0
	v_mov_b32_e32 v98, v0
	v_mov_b32_e32 v99, v0
	v_mov_b32_e32 v100, v0
	v_mov_b32_e32 v101, v0
	v_mov_b32_e32 v102, v0
	v_mov_b32_e32 v103, v0
	v_mov_b32_e32 v112, v0
	v_mov_b32_e32 v113, v0
	v_mov_b32_e32 v114, v0
	v_mov_b32_e32 v115, v0
	v_mov_b32_e32 v116, v0
	v_mov_b32_e32 v117, v0
	v_mov_b32_e32 v118, v0
	v_mov_b32_e32 v119, v0
	v_mov_b32_e32 v120, v0
	v_mov_b32_e32 v121, v0
	v_mov_b32_e32 v122, v0
	v_mov_b32_e32 v123, v0
	v_mov_b32_e32 v124, v0
	v_mov_b32_e32 v125, v0
	v_mov_b32_e32 v126, v0
	v_mov_b32_e32 v127, v0
	.p2align 6

.LBB0_678:
	s_ashr_i32 s41, s40, 31
	s_lshl_b64 s[42:43], s[40:41], 19
	s_add_u32 s42, s54, s42
	s_addc_u32 s43, s55, s43
	s_and_b64 s[44:45], s[4:5], exec
	s_cselect_b32 s41, s43, s49
	s_cselect_b32 s79, s42, s48
	s_ashr_i32 s39, s38, 31
	s_lshl_b64 s[44:45], s[38:39], 19
	s_add_u32 s44, s56, s44
	s_addc_u32 s45, s57, s45
	s_and_b64 s[52:53], s[4:5], exec
	s_cselect_b32 s39, s45, s51
	s_cselect_b32 s80, s44, s50
	s_add_u32 s48, s48, 0x40080
	s_addc_u32 s49, s49, 0
	s_add_u32 s81, s50, 0x100
	v_mov_b32_e32 v0, 0
	s_addc_u32 s82, s51, 0
	s_mov_b32 s83, -2
	v_mov_b32_e32 v1, v0
	v_mov_b32_e32 v2, v0
	v_mov_b32_e32 v3, v0
	v_mov_b32_e32 v4, v0
	v_mov_b32_e32 v5, v0
	v_mov_b32_e32 v6, v0
	v_mov_b32_e32 v7, v0
	v_mov_b32_e32 v16, v0
	v_mov_b32_e32 v17, v0
	v_mov_b32_e32 v18, v0
	v_mov_b32_e32 v19, v0
	v_mov_b32_e32 v20, v0
	v_mov_b32_e32 v21, v0
	v_mov_b32_e32 v22, v0
	v_mov_b32_e32 v23, v0
	v_mov_b32_e32 v32, v0
	v_mov_b32_e32 v33, v0
	v_mov_b32_e32 v34, v0
	v_mov_b32_e32 v35, v0
	v_mov_b32_e32 v36, v0
	v_mov_b32_e32 v37, v0
	v_mov_b32_e32 v38, v0
	v_mov_b32_e32 v39, v0
	v_mov_b32_e32 v48, v0
	v_mov_b32_e32 v49, v0
	v_mov_b32_e32 v50, v0
	v_mov_b32_e32 v51, v0
	v_mov_b32_e32 v52, v0
	v_mov_b32_e32 v53, v0
	v_mov_b32_e32 v54, v0
	v_mov_b32_e32 v55, v0
	v_mov_b32_e32 v8, v0
	v_mov_b32_e32 v9, v0
	v_mov_b32_e32 v10, v0
	v_mov_b32_e32 v11, v0
	v_mov_b32_e32 v12, v0
	v_mov_b32_e32 v13, v0
	v_mov_b32_e32 v14, v0
	v_mov_b32_e32 v15, v0
	v_mov_b32_e32 v24, v0
	v_mov_b32_e32 v25, v0
	v_mov_b32_e32 v26, v0
	v_mov_b32_e32 v27, v0
	v_mov_b32_e32 v28, v0
	v_mov_b32_e32 v29, v0
	v_mov_b32_e32 v30, v0
	v_mov_b32_e32 v31, v0
	v_mov_b32_e32 v40, v0
	v_mov_b32_e32 v41, v0
	v_mov_b32_e32 v42, v0
	v_mov_b32_e32 v43, v0
	v_mov_b32_e32 v44, v0
	v_mov_b32_e32 v45, v0
	v_mov_b32_e32 v46, v0
	v_mov_b32_e32 v47, v0
	v_mov_b32_e32 v56, v0
	v_mov_b32_e32 v57, v0
	v_mov_b32_e32 v58, v0
	v_mov_b32_e32 v59, v0
	v_mov_b32_e32 v60, v0
	v_mov_b32_e32 v61, v0
	v_mov_b32_e32 v62, v0
	v_mov_b32_e32 v63, v0
	v_mov_b32_e32 v64, v0
	v_mov_b32_e32 v65, v0
	v_mov_b32_e32 v66, v0
	v_mov_b32_e32 v67, v0
	v_mov_b32_e32 v68, v0
	v_mov_b32_e32 v69, v0
	v_mov_b32_e32 v70, v0
	v_mov_b32_e32 v71, v0
	v_mov_b32_e32 v80, v0
	v_mov_b32_e32 v81, v0
	v_mov_b32_e32 v82, v0
	v_mov_b32_e32 v83, v0
	v_mov_b32_e32 v84, v0
	v_mov_b32_e32 v85, v0
	v_mov_b32_e32 v86, v0
	v_mov_b32_e32 v87, v0
	v_mov_b32_e32 v96, v0
	v_mov_b32_e32 v97, v0
	v_mov_b32_e32 v98, v0
	v_mov_b32_e32 v99, v0
	v_mov_b32_e32 v100, v0
	v_mov_b32_e32 v101, v0
	v_mov_b32_e32 v102, v0
	v_mov_b32_e32 v103, v0
	v_mov_b32_e32 v112, v0
	v_mov_b32_e32 v113, v0
	v_mov_b32_e32 v114, v0
	v_mov_b32_e32 v115, v0
	v_mov_b32_e32 v116, v0
	v_mov_b32_e32 v117, v0
	v_mov_b32_e32 v118, v0
	v_mov_b32_e32 v119, v0
	v_mov_b32_e32 v72, v0
	v_mov_b32_e32 v73, v0
	v_mov_b32_e32 v74, v0
	v_mov_b32_e32 v75, v0
	v_mov_b32_e32 v76, v0
	v_mov_b32_e32 v77, v0
	v_mov_b32_e32 v78, v0
	v_mov_b32_e32 v79, v0
	v_mov_b32_e32 v88, v0
	v_mov_b32_e32 v89, v0
	v_mov_b32_e32 v90, v0
	v_mov_b32_e32 v91, v0
	v_mov_b32_e32 v92, v0
	v_mov_b32_e32 v93, v0
	v_mov_b32_e32 v94, v0
	v_mov_b32_e32 v95, v0
	v_mov_b32_e32 v104, v0
	v_mov_b32_e32 v105, v0
	v_mov_b32_e32 v106, v0
	v_mov_b32_e32 v107, v0
	v_mov_b32_e32 v108, v0
	v_mov_b32_e32 v109, v0
	v_mov_b32_e32 v110, v0
	v_mov_b32_e32 v111, v0
	v_mov_b32_e32 v120, v0
	v_mov_b32_e32 v121, v0
	v_mov_b32_e32 v122, v0
	v_mov_b32_e32 v123, v0
	v_mov_b32_e32 v124, v0
	v_mov_b32_e32 v125, v0
	v_mov_b32_e32 v126, v0
	v_mov_b32_e32 v127, v0
	.p2align 6

.Lsk8_zero:
	v_mov_b32_e32 v0, 0
	v_mov_b32_e32 v1, v0
	v_mov_b32_e32 v2, v0
	v_mov_b32_e32 v3, v0
	v_mov_b32_e32 v4, v0
	v_mov_b32_e32 v5, v0
	v_mov_b32_e32 v6, v0
	v_mov_b32_e32 v7, v0
	v_mov_b32_e32 v8, v0
	v_mov_b32_e32 v9, v0
	v_mov_b32_e32 v10, v0
	v_mov_b32_e32 v11, v0
	v_mov_b32_e32 v12, v0
	v_mov_b32_e32 v13, v0
	v_mov_b32_e32 v14, v0
	v_mov_b32_e32 v15, v0
	v_mov_b32_e32 v24, v0
	v_mov_b32_e32 v25, v0
	v_mov_b32_e32 v26, v0
	v_mov_b32_e32 v27, v0
	v_mov_b32_e32 v28, v0
	v_mov_b32_e32 v29, v0
	v_mov_b32_e32 v30, v0
	v_mov_b32_e32 v31, v0
	v_mov_b32_e32 v40, v0
	v_mov_b32_e32 v41, v0
	v_mov_b32_e32 v42, v0
	v_mov_b32_e32 v43, v0
	v_mov_b32_e32 v44, v0
	v_mov_b32_e32 v45, v0
	v_mov_b32_e32 v46, v0
	v_mov_b32_e32 v47, v0
	v_mov_b32_e32 v16, v0
	v_mov_b32_e32 v17, v0
	v_mov_b32_e32 v18, v0
	v_mov_b32_e32 v19, v0
	v_mov_b32_e32 v20, v0
	v_mov_b32_e32 v21, v0
	v_mov_b32_e32 v22, v0
	v_mov_b32_e32 v23, v0
	v_mov_b32_e32 v32, v0
	v_mov_b32_e32 v33, v0
	v_mov_b32_e32 v34, v0
	v_mov_b32_e32 v35, v0
	v_mov_b32_e32 v36, v0
	v_mov_b32_e32 v37, v0
	v_mov_b32_e32 v38, v0
	v_mov_b32_e32 v39, v0
	v_mov_b32_e32 v48, v0
	v_mov_b32_e32 v49, v0
	v_mov_b32_e32 v50, v0
	v_mov_b32_e32 v51, v0
	v_mov_b32_e32 v52, v0
	v_mov_b32_e32 v53, v0
	v_mov_b32_e32 v54, v0
	v_mov_b32_e32 v55, v0
	v_mov_b32_e32 v56, v0
	v_mov_b32_e32 v57, v0
	v_mov_b32_e32 v58, v0
	v_mov_b32_e32 v59, v0
	v_mov_b32_e32 v60, v0
	v_mov_b32_e32 v61, v0
	v_mov_b32_e32 v62, v0
	v_mov_b32_e32 v63, v0
	v_mov_b32_e32 v64, v0
	v_mov_b32_e32 v65, v0
	v_mov_b32_e32 v66, v0
	v_mov_b32_e32 v67, v0
	v_mov_b32_e32 v68, v0
	v_mov_b32_e32 v69, v0
	v_mov_b32_e32 v70, v0
	v_mov_b32_e32 v71, v0
	v_mov_b32_e32 v72, v0
	v_mov_b32_e32 v73, v0
	v_mov_b32_e32 v74, v0
	v_mov_b32_e32 v75, v0
	v_mov_b32_e32 v76, v0
	v_mov_b32_e32 v77, v0
	v_mov_b32_e32 v78, v0
	v_mov_b32_e32 v79, v0
	v_mov_b32_e32 v88, v0
	v_mov_b32_e32 v89, v0
	v_mov_b32_e32 v90, v0
	v_mov_b32_e32 v91, v0
	v_mov_b32_e32 v92, v0
	v_mov_b32_e32 v93, v0
	v_mov_b32_e32 v94, v0
	v_mov_b32_e32 v95, v0
	v_mov_b32_e32 v104, v0
	v_mov_b32_e32 v105, v0
	v_mov_b32_e32 v106, v0
	v_mov_b32_e32 v107, v0
	v_mov_b32_e32 v108, v0
	v_mov_b32_e32 v109, v0
	v_mov_b32_e32 v110, v0
	v_mov_b32_e32 v111, v0
	v_mov_b32_e32 v80, v0
	v_mov_b32_e32 v81, v0
	v_mov_b32_e32 v82, v0
	v_mov_b32_e32 v83, v0
	v_mov_b32_e32 v84, v0
	v_mov_b32_e32 v85, v0
	v_mov_b32_e32 v86, v0
	v_mov_b32_e32 v87, v0
	v_mov_b32_e32 v96, v0
	v_mov_b32_e32 v97, v0
	v_mov_b32_e32 v98, v0
	v_mov_b32_e32 v99, v0
	v_mov_b32_e32 v100, v0
	v_mov_b32_e32 v101, v0
	v_mov_b32_e32 v102, v0
	v_mov_b32_e32 v103, v0
	v_mov_b32_e32 v112, v0
	v_mov_b32_e32 v113, v0
	v_mov_b32_e32 v114, v0
	v_mov_b32_e32 v115, v0
	v_mov_b32_e32 v116, v0
	v_mov_b32_e32 v117, v0
	v_mov_b32_e32 v118, v0
	v_mov_b32_e32 v119, v0
	v_mov_b32_e32 v120, v0
	v_mov_b32_e32 v121, v0
	v_mov_b32_e32 v122, v0
	v_mov_b32_e32 v123, v0
	v_mov_b32_e32 v124, v0
	v_mov_b32_e32 v125, v0
	v_mov_b32_e32 v126, v0
	v_mov_b32_e32 v127, v0
	.p2align 6

.LBB0_880:
	s_ashr_i32 s43, s42, 31
	s_lshl_b64 s[44:45], s[42:43], 19
	s_add_u32 s44, s54, s44
	s_addc_u32 s45, s55, s45
	s_and_b64 s[46:47], s[4:5], exec
	s_cselect_b32 s7, s45, s49
	s_cselect_b32 s9, s44, s48
	s_ashr_i32 s41, s40, 31
	s_lshl_b64 s[46:47], s[40:41], 19
	s_add_u32 s46, s56, s46
	s_addc_u32 s47, s57, s47
	s_and_b64 s[52:53], s[4:5], exec
	s_cselect_b32 s41, s47, s51
	s_cselect_b32 s43, s46, s50
	s_add_u32 s48, s48, 0x40080
	s_addc_u32 s49, s49, 0
	s_add_u32 s63, s50, 0x100
	v_mov_b32_e32 v0, 0
	s_addc_u32 s77, s51, 0
	s_mov_b32 s78, -2
	v_mov_b32_e32 v1, v0
	v_mov_b32_e32 v2, v0
	v_mov_b32_e32 v3, v0
	v_mov_b32_e32 v4, v0
	v_mov_b32_e32 v5, v0
	v_mov_b32_e32 v6, v0
	v_mov_b32_e32 v7, v0
	v_mov_b32_e32 v16, v0
	v_mov_b32_e32 v17, v0
	v_mov_b32_e32 v18, v0
	v_mov_b32_e32 v19, v0
	v_mov_b32_e32 v20, v0
	v_mov_b32_e32 v21, v0
	v_mov_b32_e32 v22, v0
	v_mov_b32_e32 v23, v0
	v_mov_b32_e32 v32, v0
	v_mov_b32_e32 v33, v0
	v_mov_b32_e32 v34, v0
	v_mov_b32_e32 v35, v0
	v_mov_b32_e32 v36, v0
	v_mov_b32_e32 v37, v0
	v_mov_b32_e32 v38, v0
	v_mov_b32_e32 v39, v0
	v_mov_b32_e32 v48, v0
	v_mov_b32_e32 v49, v0
	v_mov_b32_e32 v50, v0
	v_mov_b32_e32 v51, v0
	v_mov_b32_e32 v52, v0
	v_mov_b32_e32 v53, v0
	v_mov_b32_e32 v54, v0
	v_mov_b32_e32 v55, v0
	v_mov_b32_e32 v8, v0
	v_mov_b32_e32 v9, v0
	v_mov_b32_e32 v10, v0
	v_mov_b32_e32 v11, v0
	v_mov_b32_e32 v12, v0
	v_mov_b32_e32 v13, v0
	v_mov_b32_e32 v14, v0
	v_mov_b32_e32 v15, v0
	v_mov_b32_e32 v24, v0
	v_mov_b32_e32 v25, v0
	v_mov_b32_e32 v26, v0
	v_mov_b32_e32 v27, v0
	v_mov_b32_e32 v28, v0
	v_mov_b32_e32 v29, v0
	v_mov_b32_e32 v30, v0
	v_mov_b32_e32 v31, v0
	v_mov_b32_e32 v40, v0
	v_mov_b32_e32 v41, v0
	v_mov_b32_e32 v42, v0
	v_mov_b32_e32 v43, v0
	v_mov_b32_e32 v44, v0
	v_mov_b32_e32 v45, v0
	v_mov_b32_e32 v46, v0
	v_mov_b32_e32 v47, v0
	v_mov_b32_e32 v56, v0
	v_mov_b32_e32 v57, v0
	v_mov_b32_e32 v58, v0
	v_mov_b32_e32 v59, v0
	v_mov_b32_e32 v60, v0
	v_mov_b32_e32 v61, v0
	v_mov_b32_e32 v62, v0
	v_mov_b32_e32 v63, v0
	v_mov_b32_e32 v64, v0
	v_mov_b32_e32 v65, v0
	v_mov_b32_e32 v66, v0
	v_mov_b32_e32 v67, v0
	v_mov_b32_e32 v68, v0
	v_mov_b32_e32 v69, v0
	v_mov_b32_e32 v70, v0
	v_mov_b32_e32 v71, v0
	v_mov_b32_e32 v80, v0
	v_mov_b32_e32 v81, v0
	v_mov_b32_e32 v82, v0
	v_mov_b32_e32 v83, v0
	v_mov_b32_e32 v84, v0
	v_mov_b32_e32 v85, v0
	v_mov_b32_e32 v86, v0
	v_mov_b32_e32 v87, v0
	v_mov_b32_e32 v96, v0
	v_mov_b32_e32 v97, v0
	v_mov_b32_e32 v98, v0
	v_mov_b32_e32 v99, v0
	v_mov_b32_e32 v100, v0
	v_mov_b32_e32 v101, v0
	v_mov_b32_e32 v102, v0
	v_mov_b32_e32 v103, v0
	v_mov_b32_e32 v112, v0
	v_mov_b32_e32 v113, v0
	v_mov_b32_e32 v114, v0
	v_mov_b32_e32 v115, v0
	v_mov_b32_e32 v116, v0
	v_mov_b32_e32 v117, v0
	v_mov_b32_e32 v118, v0
	v_mov_b32_e32 v119, v0
	v_mov_b32_e32 v72, v0
	v_mov_b32_e32 v73, v0
	v_mov_b32_e32 v74, v0
	v_mov_b32_e32 v75, v0
	v_mov_b32_e32 v76, v0
	v_mov_b32_e32 v77, v0
	v_mov_b32_e32 v78, v0
	v_mov_b32_e32 v79, v0
	v_mov_b32_e32 v88, v0
	v_mov_b32_e32 v89, v0
	v_mov_b32_e32 v90, v0
	v_mov_b32_e32 v91, v0
	v_mov_b32_e32 v92, v0
	v_mov_b32_e32 v93, v0
	v_mov_b32_e32 v94, v0
	v_mov_b32_e32 v95, v0
	v_mov_b32_e32 v104, v0
	v_mov_b32_e32 v105, v0
	v_mov_b32_e32 v106, v0
	v_mov_b32_e32 v107, v0
	v_mov_b32_e32 v108, v0
	v_mov_b32_e32 v109, v0
	v_mov_b32_e32 v110, v0
	v_mov_b32_e32 v111, v0
	v_mov_b32_e32 v120, v0
	v_mov_b32_e32 v121, v0
	v_mov_b32_e32 v122, v0
	v_mov_b32_e32 v123, v0
	v_mov_b32_e32 v124, v0
	v_mov_b32_e32 v125, v0
	v_mov_b32_e32 v126, v0
	v_mov_b32_e32 v127, v0
	.p2align 6

.LBB0_1143:
	s_ashr_i32 s31, s30, 31
	s_lshl_b64 s[38:39], s[30:31], 19
	s_add_u32 s38, s48, s38
	s_addc_u32 s39, s49, s39
	s_and_b64 s[40:41], s[4:5], exec
	s_cselect_b32 s31, s39, s43
	s_cselect_b32 s71, s38, s42
	s_ashr_i32 s35, s34, 31
	s_lshl_b64 s[40:41], s[34:35], 19
	s_add_u32 s40, s50, s40
	s_addc_u32 s41, s51, s41
	s_and_b64 s[46:47], s[4:5], exec
	s_cselect_b32 s35, s41, s45
	s_cselect_b32 s72, s40, s44
	s_add_u32 s42, s42, 0x40080
	s_addc_u32 s43, s43, 0
	s_add_u32 s73, s44, 0x100
	v_mov_b32_e32 v0, 0
	s_addc_u32 s74, s45, 0
	s_mov_b32 s75, -2
	v_mov_b32_e32 v1, v0
	v_mov_b32_e32 v2, v0
	v_mov_b32_e32 v3, v0
	v_mov_b32_e32 v4, v0
	v_mov_b32_e32 v5, v0
	v_mov_b32_e32 v6, v0
	v_mov_b32_e32 v7, v0
	v_mov_b32_e32 v8, v0
	v_mov_b32_e32 v9, v0
	v_mov_b32_e32 v10, v0
	v_mov_b32_e32 v11, v0
	v_mov_b32_e32 v12, v0
	v_mov_b32_e32 v13, v0
	v_mov_b32_e32 v14, v0
	v_mov_b32_e32 v15, v0
	v_mov_b32_e32 v24, v0
	v_mov_b32_e32 v25, v0
	v_mov_b32_e32 v26, v0
	v_mov_b32_e32 v27, v0
	v_mov_b32_e32 v28, v0
	v_mov_b32_e32 v29, v0
	v_mov_b32_e32 v30, v0
	v_mov_b32_e32 v31, v0
	v_mov_b32_e32 v40, v0
	v_mov_b32_e32 v41, v0
	v_mov_b32_e32 v42, v0
	v_mov_b32_e32 v43, v0
	v_mov_b32_e32 v44, v0
	v_mov_b32_e32 v45, v0
	v_mov_b32_e32 v46, v0
	v_mov_b32_e32 v47, v0
	v_mov_b32_e32 v16, v0
	v_mov_b32_e32 v17, v0
	v_mov_b32_e32 v18, v0
	v_mov_b32_e32 v19, v0
	v_mov_b32_e32 v20, v0
	v_mov_b32_e32 v21, v0
	v_mov_b32_e32 v22, v0
	v_mov_b32_e32 v23, v0
	v_mov_b32_e32 v32, v0
	v_mov_b32_e32 v33, v0
	v_mov_b32_e32 v34, v0
	v_mov_b32_e32 v35, v0
	v_mov_b32_e32 v36, v0
	v_mov_b32_e32 v37, v0
	v_mov_b32_e32 v38, v0
	v_mov_b32_e32 v39, v0
	v_mov_b32_e32 v48, v0
	v_mov_b32_e32 v49, v0
	v_mov_b32_e32 v50, v0
	v_mov_b32_e32 v51, v0
	v_mov_b32_e32 v52, v0
	v_mov_b32_e32 v53, v0
	v_mov_b32_e32 v54, v0
	v_mov_b32_e32 v55, v0
	v_mov_b32_e32 v56, v0
	v_mov_b32_e32 v57, v0
	v_mov_b32_e32 v58, v0
	v_mov_b32_e32 v59, v0
	v_mov_b32_e32 v60, v0
	v_mov_b32_e32 v61, v0
	v_mov_b32_e32 v62, v0
	v_mov_b32_e32 v63, v0
	v_mov_b32_e32 v64, v0
	v_mov_b32_e32 v65, v0
	v_mov_b32_e32 v66, v0
	v_mov_b32_e32 v67, v0
	v_mov_b32_e32 v68, v0
	v_mov_b32_e32 v69, v0
	v_mov_b32_e32 v70, v0
	v_mov_b32_e32 v71, v0
	v_mov_b32_e32 v72, v0
	v_mov_b32_e32 v73, v0
	v_mov_b32_e32 v74, v0
	v_mov_b32_e32 v75, v0
	v_mov_b32_e32 v76, v0
	v_mov_b32_e32 v77, v0
	v_mov_b32_e32 v78, v0
	v_mov_b32_e32 v79, v0
	v_mov_b32_e32 v88, v0
	v_mov_b32_e32 v89, v0
	v_mov_b32_e32 v90, v0
	v_mov_b32_e32 v91, v0
	v_mov_b32_e32 v92, v0
	v_mov_b32_e32 v93, v0
	v_mov_b32_e32 v94, v0
	v_mov_b32_e32 v95, v0
	v_mov_b32_e32 v104, v0
	v_mov_b32_e32 v105, v0
	v_mov_b32_e32 v106, v0
	v_mov_b32_e32 v107, v0
	v_mov_b32_e32 v108, v0
	v_mov_b32_e32 v109, v0
	v_mov_b32_e32 v110, v0
	v_mov_b32_e32 v111, v0
	v_mov_b32_e32 v80, v0
	v_mov_b32_e32 v81, v0
	v_mov_b32_e32 v82, v0
	v_mov_b32_e32 v83, v0
	v_mov_b32_e32 v84, v0
	v_mov_b32_e32 v85, v0
	v_mov_b32_e32 v86, v0
	v_mov_b32_e32 v87, v0
	v_mov_b32_e32 v96, v0
	v_mov_b32_e32 v97, v0
	v_mov_b32_e32 v98, v0
	v_mov_b32_e32 v99, v0
	v_mov_b32_e32 v100, v0
	v_mov_b32_e32 v101, v0
	v_mov_b32_e32 v102, v0
	v_mov_b32_e32 v103, v0
	v_mov_b32_e32 v112, v0
	v_mov_b32_e32 v113, v0
	v_mov_b32_e32 v114, v0
	v_mov_b32_e32 v115, v0
	v_mov_b32_e32 v116, v0
	v_mov_b32_e32 v117, v0
	v_mov_b32_e32 v118, v0
	v_mov_b32_e32 v119, v0
	v_mov_b32_e32 v120, v0
	v_mov_b32_e32 v121, v0
	v_mov_b32_e32 v122, v0
	v_mov_b32_e32 v123, v0
	v_mov_b32_e32 v124, v0
	v_mov_b32_e32 v125, v0
	v_mov_b32_e32 v126, v0
	v_mov_b32_e32 v127, v0
	.p2align 6

.LBB0_1302:
	s_ashr_i32 s31, s30, 31
	s_lshl_b64 s[34:35], s[30:31], 19
	s_add_u32 s34, s47, s34
	s_addc_u32 s35, s48, s35
	s_and_b64 s[36:37], s[4:5], exec
	s_cselect_b32 s31, s35, s41
	s_cselect_b32 s71, s34, s40
	s_ashr_i32 s29, s28, 31
	s_lshl_b64 s[36:37], s[28:29], 19
	s_add_u32 s36, s49, s36
	s_addc_u32 s37, s50, s37
	s_and_b64 s[44:45], s[4:5], exec
	s_cselect_b32 s29, s37, s43
	s_cselect_b32 s72, s36, s42
	s_add_u32 s40, s40, 0x40080
	s_addc_u32 s41, s41, 0
	s_add_u32 s73, s42, 0x100
	v_mov_b32_e32 v0, 0
	s_addc_u32 s74, s43, 0
	s_mov_b32 s75, -2
	v_mov_b32_e32 v1, v0
	v_mov_b32_e32 v2, v0
	v_mov_b32_e32 v3, v0
	v_mov_b32_e32 v4, v0
	v_mov_b32_e32 v5, v0
	v_mov_b32_e32 v6, v0
	v_mov_b32_e32 v7, v0
	v_mov_b32_e32 v16, v0
	v_mov_b32_e32 v17, v0
	v_mov_b32_e32 v18, v0
	v_mov_b32_e32 v19, v0
	v_mov_b32_e32 v20, v0
	v_mov_b32_e32 v21, v0
	v_mov_b32_e32 v22, v0
	v_mov_b32_e32 v23, v0
	v_mov_b32_e32 v32, v0
	v_mov_b32_e32 v33, v0
	v_mov_b32_e32 v34, v0
	v_mov_b32_e32 v35, v0
	v_mov_b32_e32 v36, v0
	v_mov_b32_e32 v37, v0
	v_mov_b32_e32 v38, v0
	v_mov_b32_e32 v39, v0
	v_mov_b32_e32 v48, v0
	v_mov_b32_e32 v49, v0
	v_mov_b32_e32 v50, v0
	v_mov_b32_e32 v51, v0
	v_mov_b32_e32 v52, v0
	v_mov_b32_e32 v53, v0
	v_mov_b32_e32 v54, v0
	v_mov_b32_e32 v55, v0
	v_mov_b32_e32 v8, v0
	v_mov_b32_e32 v9, v0
	v_mov_b32_e32 v10, v0
	v_mov_b32_e32 v11, v0
	v_mov_b32_e32 v12, v0
	v_mov_b32_e32 v13, v0
	v_mov_b32_e32 v14, v0
	v_mov_b32_e32 v15, v0
	v_mov_b32_e32 v24, v0
	v_mov_b32_e32 v25, v0
	v_mov_b32_e32 v26, v0
	v_mov_b32_e32 v27, v0
	v_mov_b32_e32 v28, v0
	v_mov_b32_e32 v29, v0
	v_mov_b32_e32 v30, v0
	v_mov_b32_e32 v31, v0
	v_mov_b32_e32 v40, v0
	v_mov_b32_e32 v41, v0
	v_mov_b32_e32 v42, v0
	v_mov_b32_e32 v43, v0
	v_mov_b32_e32 v44, v0
	v_mov_b32_e32 v45, v0
	v_mov_b32_e32 v46, v0
	v_mov_b32_e32 v47, v0
	v_mov_b32_e32 v56, v0
	v_mov_b32_e32 v57, v0
	v_mov_b32_e32 v58, v0
	v_mov_b32_e32 v59, v0
	v_mov_b32_e32 v60, v0
	v_mov_b32_e32 v61, v0
	v_mov_b32_e32 v62, v0
	v_mov_b32_e32 v63, v0
	v_mov_b32_e32 v64, v0
	v_mov_b32_e32 v65, v0
	v_mov_b32_e32 v66, v0
	v_mov_b32_e32 v67, v0
	v_mov_b32_e32 v68, v0
	v_mov_b32_e32 v69, v0
	v_mov_b32_e32 v70, v0
	v_mov_b32_e32 v71, v0
	v_mov_b32_e32 v80, v0
	v_mov_b32_e32 v81, v0
	v_mov_b32_e32 v82, v0
	v_mov_b32_e32 v83, v0
	v_mov_b32_e32 v84, v0
	v_mov_b32_e32 v85, v0
	v_mov_b32_e32 v86, v0
	v_mov_b32_e32 v87, v0
	v_mov_b32_e32 v96, v0
	v_mov_b32_e32 v97, v0
	v_mov_b32_e32 v98, v0
	v_mov_b32_e32 v99, v0
	v_mov_b32_e32 v100, v0
	v_mov_b32_e32 v101, v0
	v_mov_b32_e32 v102, v0
	v_mov_b32_e32 v103, v0
	v_mov_b32_e32 v112, v0
	v_mov_b32_e32 v113, v0
	v_mov_b32_e32 v114, v0
	v_mov_b32_e32 v115, v0
	v_mov_b32_e32 v116, v0
	v_mov_b32_e32 v117, v0
	v_mov_b32_e32 v118, v0
	v_mov_b32_e32 v119, v0
	v_mov_b32_e32 v72, v0
	v_mov_b32_e32 v73, v0
	v_mov_b32_e32 v74, v0
	v_mov_b32_e32 v75, v0
	v_mov_b32_e32 v76, v0
	v_mov_b32_e32 v77, v0
	v_mov_b32_e32 v78, v0
	v_mov_b32_e32 v79, v0
	v_mov_b32_e32 v88, v0
	v_mov_b32_e32 v89, v0
	v_mov_b32_e32 v90, v0
	v_mov_b32_e32 v91, v0
	v_mov_b32_e32 v92, v0
	v_mov_b32_e32 v93, v0
	v_mov_b32_e32 v94, v0
	v_mov_b32_e32 v95, v0
	v_mov_b32_e32 v104, v0
	v_mov_b32_e32 v105, v0
	v_mov_b32_e32 v106, v0
	v_mov_b32_e32 v107, v0
	v_mov_b32_e32 v108, v0
	v_mov_b32_e32 v109, v0
	v_mov_b32_e32 v110, v0
	v_mov_b32_e32 v111, v0
	v_mov_b32_e32 v120, v0
	v_mov_b32_e32 v121, v0
	v_mov_b32_e32 v122, v0
	v_mov_b32_e32 v123, v0
	v_mov_b32_e32 v124, v0
	v_mov_b32_e32 v125, v0
	v_mov_b32_e32 v126, v0
	v_mov_b32_e32 v127, v0
	.p2align 6
